# diff-attn in-order waves (0-3): next-stage LDS-DMA issued between softmax and P.V instead of at the stage head (on top of own-block reversed tile order)
# speedup vs baseline: 1.0132x; 1.0022x over previous
; DI f32x16 mfma32(bf16x8 a, bf16x8 b, f32x16 c) { return __builtin_amdgcn_mfma_f32_32x32x16_bf16(a, b, c, 0, 0, 0); }
; #define DF_VLD(VF, VOFF, H) do { _Pragma("unroll") for (int d2 = 0; d2 < 2; ++d2) { LAS unsigned char* vb_ = lds3 + (VOFF) + (2 * (H) + d2) * 4096; VF[2 * d2] = vfrag(vb_); VF[2 * d2 + 1] = vfrag(vb_ + 1024); } } while (0)
; #define DF_PVM(VF, P0, P1, H) do { _Pragma("unroll") for (int d2 = 0; d2 < 2; ++d2) { o[2 * (H) + d2] = mfma32(VF[2 * d2], P0, o[2 * (H) + d2]); o[2 * (H) + d2] = mfma32(VF[2 * d2 + 1], P1, o[2 * (H) + d2]); } } while (0)
; DI void diff_stage(const unsigned char* lds, LAS unsigned char* lds3, int buf, int t, int comp, int q0, int r32, int hi, int vlane, bool skew,
;                    const bf16x8 (&qf)[4], f32x16 (&o)[4], float& m, float& l, bf16x8 (&pp)[4], int& pvo, bool& have_prev) {
;     const int k0 = 64 * t;
;     if (k0 > q0 + 31) return;
;     const unsigned char* sb = lds + buf * DF_STAGE + comp * DF_K2 + r32 * 128; const int ke16 = (hi ^ ((r32 >> 1) & 7)) * 16;
;     bf16x8 vf[4];
;     if (skew && have_prev) {
; #pragma unroll
;         for (int sub = 0; sub < 2; ++sub) { DF_VLD(vf, pvo + sub * 2048, 0); DF_PVM(vf, pp[2 * sub], pp[2 * sub + 1], 0); DF_VLD(vf, pvo + sub * 2048, 1); DF_PVM(vf, pp[2 * sub], pp[2 * sub + 1], 1); }
;     }
;     f32x16 s0, s1;
; #pragma unroll
;     for (int i = 0; i < 16; ++i) { s0[i] = 0.f; s1[i] = 0.f; }
;     {
;         bf16x8 k0f[4], k1f[4];
; #pragma unroll
;         for (int c = 0; c < 4; ++c) { k0f[c] = *(const bf16x8*)(sb + ((32 * c) ^ ke16)); k1f[c] = *(const bf16x8*)(sb + 32 * 128 + ((32 * c) ^ ke16)); }
; #pragma unroll
;         for (int c = 0; c < 4; ++c) { s0 = mfma32(k0f[c], qf[c], s0); s1 = mfma32(k1f[c], qf[c], s1); }
;     }
;     if (k0 + 63 > q0) {
;         const int dq = q0 + r32 - k0 - 4 * hi;
; #pragma unroll
;         for (int i = 0; i < 16; ++i) { const int ci = (i & 3) + 8 * (i >> 2); s0[i] = (ci > dq) ? -INFINITY : s0[i]; s1[i] = (ci + 32 > dq) ? -INFINITY : s1[i]; }
;     }
.Ldf1a_loop:
	s_sub_i32 s71, s8, 63
	s_cmp_gt_u32 s71, s53
	s_cbranch_scc1 .Ldf1a_skip
	s_and_b32 s55, s11, 0x18000
	v_add_u32_e32 v2, s55, v160
	v_add_u32_e32 v3, v2, v161
	v_add_u32_e32 v4, v2, v162
	v_add_u32_e32 v5, v2, v163
	v_add_u32_e32 v2, v2, v164
	ds_read_b128 v[208:211], v3
	ds_read_b128 v[212:215], v3 offset:4096
	ds_read_b128 v[216:219], v4
	ds_read_b128 v[220:223], v4 offset:4096
	ds_read_b128 v[224:227], v5
	ds_read_b128 v[228:231], v5 offset:4096
	ds_read_b128 v[232:235], v2
	ds_read_b128 v[236:239], v2 offset:4096
	v_add_u32_e32 v6, s55, v165
	s_waitcnt lgkmcnt(7)
	v_mfma_f32_32x32x16_bf16 v[96:111], v[208:211], v[124:127], 0
	s_waitcnt lgkmcnt(6)
	v_mfma_f32_32x32x16_bf16 v[80:95], v[212:215], v[124:127], 0
	s_waitcnt lgkmcnt(5)
	v_mfma_f32_32x32x16_bf16 v[96:111], v[216:219], v[120:123], v[96:111]
	s_waitcnt lgkmcnt(4)
	v_mfma_f32_32x32x16_bf16 v[80:95], v[220:223], v[120:123], v[80:95]
	s_waitcnt lgkmcnt(3)
	v_mfma_f32_32x32x16_bf16 v[96:111], v[224:227], v[116:119], v[96:111]
	s_waitcnt lgkmcnt(2)
	v_mfma_f32_32x32x16_bf16 v[80:95], v[228:231], v[116:119], v[80:95]
	s_waitcnt lgkmcnt(1)
	v_mfma_f32_32x32x16_bf16 v[96:111], v[232:235], v[112:115], v[96:111]
	s_waitcnt lgkmcnt(0)
	v_mfma_f32_32x32x16_bf16 v[80:95], v[236:239], v[112:115], v[80:95]
	ds_read_b64_tr_b16 v[208:209], v6 offset:16384
	ds_read_b64_tr_b16 v[210:211], v6 offset:16896
	ds_read_b64_tr_b16 v[212:213], v6 offset:17408
	ds_read_b64_tr_b16 v[214:215], v6 offset:17920
	ds_read_b64_tr_b16 v[216:217], v6 offset:20480
	ds_read_b64_tr_b16 v[218:219], v6 offset:20992
	ds_read_b64_tr_b16 v[220:221], v6 offset:21504
	ds_read_b64_tr_b16 v[222:223], v6 offset:22016
	ds_read_b64_tr_b16 v[224:225], v6 offset:24576
	ds_read_b64_tr_b16 v[226:227], v6 offset:25088
	ds_read_b64_tr_b16 v[228:229], v6 offset:25600
	ds_read_b64_tr_b16 v[230:231], v6 offset:26112
	s_cmp_le_u32 s8, s7
	s_cbranch_scc1 .Ldf1a_nodiag
	s_nop 7
	v_cmp_lt_i32_e32 vcc, -1, v146
	s_nop 1
	v_cndmask_b32_e32 v96, v176, v96, vcc
	v_cmp_lt_i32_e32 vcc, 31, v146
	s_nop 1
	v_cndmask_b32_e32 v80, v176, v80, vcc
	v_cmp_lt_i32_e32 vcc, 0, v146
	s_nop 1
	v_cndmask_b32_e32 v97, v176, v97, vcc
	v_cmp_lt_i32_e32 vcc, 32, v146
	s_nop 1
	v_cndmask_b32_e32 v81, v176, v81, vcc
	v_cmp_lt_i32_e32 vcc, 1, v146
	s_nop 1
	v_cndmask_b32_e32 v98, v176, v98, vcc
	v_cmp_lt_i32_e32 vcc, 33, v146
	s_nop 1
	v_cndmask_b32_e32 v82, v176, v82, vcc
	v_cmp_lt_i32_e32 vcc, 2, v146
	s_nop 1
	v_cndmask_b32_e32 v99, v176, v99, vcc
	v_cmp_lt_i32_e32 vcc, 34, v146
	s_nop 1
	v_cndmask_b32_e32 v83, v176, v83, vcc
	v_cmp_lt_i32_e32 vcc, 7, v146
	s_nop 1
	v_cndmask_b32_e32 v100, v176, v100, vcc
	v_cmp_lt_i32_e32 vcc, 39, v146
	s_nop 1
	v_cndmask_b32_e32 v84, v176, v84, vcc
	v_cmp_lt_i32_e32 vcc, 8, v146
	s_nop 1
	v_cndmask_b32_e32 v101, v176, v101, vcc
	v_cmp_lt_i32_e32 vcc, 40, v146
	s_nop 1
	v_cndmask_b32_e32 v85, v176, v85, vcc
	v_cmp_lt_i32_e32 vcc, 9, v146
	s_nop 1
	v_cndmask_b32_e32 v102, v176, v102, vcc
	v_cmp_lt_i32_e32 vcc, 41, v146
	s_nop 1
	v_cndmask_b32_e32 v86, v176, v86, vcc
	v_cmp_lt_i32_e32 vcc, 10, v146
	s_nop 1
	v_cndmask_b32_e32 v103, v176, v103, vcc
	v_cmp_lt_i32_e32 vcc, 42, v146
	s_nop 1
	v_cndmask_b32_e32 v87, v176, v87, vcc
	v_cmp_lt_i32_e32 vcc, 15, v146
	s_nop 1
	v_cndmask_b32_e32 v104, v176, v104, vcc
	v_cmp_lt_i32_e32 vcc, 47, v146
	s_nop 1
	v_cndmask_b32_e32 v88, v176, v88, vcc
	v_cmp_lt_i32_e32 vcc, 16, v146
	s_nop 1
	v_cndmask_b32_e32 v105, v176, v105, vcc
	v_cmp_lt_i32_e32 vcc, 48, v146
	s_nop 1
	v_cndmask_b32_e32 v89, v176, v89, vcc
	v_cmp_lt_i32_e32 vcc, 17, v146
	s_nop 1
	v_cndmask_b32_e32 v106, v176, v106, vcc
	v_cmp_lt_i32_e32 vcc, 49, v146
	s_nop 1
	v_cndmask_b32_e32 v90, v176, v90, vcc
	v_cmp_lt_i32_e32 vcc, 18, v146
	s_nop 1
	v_cndmask_b32_e32 v107, v176, v107, vcc
	v_cmp_lt_i32_e32 vcc, 50, v146
	s_nop 1
	v_cndmask_b32_e32 v91, v176, v91, vcc
	v_cmp_lt_i32_e32 vcc, 23, v146
	s_nop 1
	v_cndmask_b32_e32 v108, v176, v108, vcc
	v_cmp_lt_i32_e32 vcc, 55, v146
	s_nop 1
	v_cndmask_b32_e32 v92, v176, v92, vcc
	v_cmp_lt_i32_e32 vcc, 24, v146
	s_nop 1
	v_cndmask_b32_e32 v109, v176, v109, vcc
	v_cmp_lt_i32_e32 vcc, 56, v146
	s_nop 1
	v_cndmask_b32_e32 v93, v176, v93, vcc
	v_cmp_lt_i32_e32 vcc, 25, v146
	s_nop 1
	v_cndmask_b32_e32 v110, v176, v110, vcc
	v_cmp_lt_i32_e32 vcc, 57, v146
	s_nop 1
	v_cndmask_b32_e32 v94, v176, v94, vcc
	v_cmp_lt_i32_e32 vcc, 26, v146
	s_nop 1
	v_cndmask_b32_e32 v111, v176, v111, vcc
	v_cmp_lt_i32_e32 vcc, 58, v146
	s_nop 1
	v_cndmask_b32_e32 v95, v176, v95, vcc

; DI float fexp2(float x) { return __builtin_amdgcn_exp2f(x); }
; #define DF_VLD(VF, VOFF, H) do { _Pragma("unroll") for (int d2 = 0; d2 < 2; ++d2) { LAS unsigned char* vb_ = lds3 + (VOFF) + (2 * (H) + d2) * 4096; VF[2 * d2] = vfrag(vb_); VF[2 * d2 + 1] = vfrag(vb_ + 1024); } } while (0)
; #define DF_PVM(VF, P0, P1, H) do { _Pragma("unroll") for (int d2 = 0; d2 < 2; ++d2) { o[2 * (H) + d2] = mfma32(VF[2 * d2], P0, o[2 * (H) + d2]); o[2 * (H) + d2] = mfma32(VF[2 * d2 + 1], P1, o[2 * (H) + d2]); } } while (0)
; DI void diff_stage(const unsigned char* lds, LAS unsigned char* lds3, int buf, int t, int comp, int q0, int r32, int hi, int vlane, bool skew,
;                    const bf16x8 (&qf)[4], f32x16 (&o)[4], float& m, float& l, bf16x8 (&pp)[4], int& pvo, bool& have_prev) {
;     ...
;     float sum0 = 0.f, sum1 = 0.f;
; #pragma unroll
;     for (int i = 0; i < 16; ++i) { s0[i] = fexp2(__builtin_fmaf(s0[i], SCL2, -m)); sum0 += s0[i]; s1[i] = fexp2(__builtin_fmaf(s1[i], SCL2, -m)); sum1 += s1[i]; }
;     l += sum0 + sum1;
;     const int vo = buf * DF_STAGE + DF_V + vlane;
;     if (!skew) {
;         const bf16x8 p00 = packP<0>(s0), p01 = packP<1>(s0);
;         DF_VLD(vf, vo, 0); DF_PVM(vf, p00, p01, 0); DF_VLD(vf, vo, 1); DF_PVM(vf, p00, p01, 1);
;         const bf16x8 p10 = packP<0>(s1), p11 = packP<1>(s1);
;         DF_VLD(vf, vo + 2048, 0); DF_PVM(vf, p10, p11, 0); DF_VLD(vf, vo + 2048, 1); DF_PVM(vf, p10, p11, 1);
.Ldf1a_notrig:
	v_fma_f32 v96, v96, s44, -v147
	v_fma_f32 v97, v97, s44, -v147
	v_exp_f32_e32 v96, v96
	v_exp_f32_e32 v97, v97
	v_fma_f32 v98, v98, s44, -v147
	v_fma_f32 v99, v99, s44, -v147
	v_exp_f32_e32 v98, v98
	v_exp_f32_e32 v99, v99
	v_fma_f32 v100, v100, s44, -v147
	v_fma_f32 v101, v101, s44, -v147
	v_exp_f32_e32 v100, v100
	v_exp_f32_e32 v101, v101
	v_fma_f32 v102, v102, s44, -v147
	v_fma_f32 v103, v103, s44, -v147
	v_exp_f32_e32 v102, v102
	v_exp_f32_e32 v103, v103
	v_fma_f32 v104, v104, s44, -v147
	v_fma_f32 v105, v105, s44, -v147
	v_exp_f32_e32 v104, v104
	v_exp_f32_e32 v105, v105
	v_fma_f32 v106, v106, s44, -v147
	v_fma_f32 v107, v107, s44, -v147
	v_exp_f32_e32 v106, v106
	v_exp_f32_e32 v107, v107
	v_fma_f32 v108, v108, s44, -v147
	v_fma_f32 v109, v109, s44, -v147
	v_exp_f32_e32 v108, v108
	v_exp_f32_e32 v109, v109
	v_fma_f32 v110, v110, s44, -v147
	v_fma_f32 v111, v111, s44, -v147
	v_exp_f32_e32 v110, v110
	v_exp_f32_e32 v111, v111
	v_add_f32_e32 v14, v96, v97
	v_add_f32_e32 v14, v14, v98
	v_add_f32_e32 v14, v14, v99
	v_add_f32_e32 v14, v14, v100
	v_add_f32_e32 v14, v14, v101
	v_add_f32_e32 v14, v14, v102
	v_add_f32_e32 v14, v14, v103
	v_add_f32_e32 v14, v14, v104
	v_add_f32_e32 v14, v14, v105
	v_add_f32_e32 v14, v14, v106
	v_add_f32_e32 v14, v14, v107
	v_add_f32_e32 v14, v14, v108
	v_add_f32_e32 v14, v14, v109
	v_add_f32_e32 v14, v14, v110
	v_add_f32_e32 v14, v14, v111
	v_fma_f32 v80, v80, s44, -v147
	v_fma_f32 v81, v81, s44, -v147
	v_exp_f32_e32 v80, v80
	v_exp_f32_e32 v81, v81
	v_fma_f32 v82, v82, s44, -v147
	v_fma_f32 v83, v83, s44, -v147
	v_exp_f32_e32 v82, v82
	v_exp_f32_e32 v83, v83
	v_fma_f32 v84, v84, s44, -v147
	v_fma_f32 v85, v85, s44, -v147
	v_exp_f32_e32 v84, v84
	v_exp_f32_e32 v85, v85
	v_fma_f32 v86, v86, s44, -v147
	v_fma_f32 v87, v87, s44, -v147
	v_exp_f32_e32 v86, v86
	v_exp_f32_e32 v87, v87
	v_fma_f32 v88, v88, s44, -v147
	v_fma_f32 v89, v89, s44, -v147
	v_exp_f32_e32 v88, v88
	v_exp_f32_e32 v89, v89
	v_fma_f32 v90, v90, s44, -v147
	v_fma_f32 v91, v91, s44, -v147
	v_exp_f32_e32 v90, v90
	v_exp_f32_e32 v91, v91
	v_fma_f32 v92, v92, s44, -v147
	v_fma_f32 v93, v93, s44, -v147
	v_exp_f32_e32 v92, v92
	v_exp_f32_e32 v93, v93
	v_fma_f32 v94, v94, s44, -v147
	v_fma_f32 v95, v95, s44, -v147
	v_exp_f32_e32 v94, v94
	v_exp_f32_e32 v95, v95
	v_add_f32_e32 v15, v80, v81
	v_add_f32_e32 v15, v15, v82
	v_add_f32_e32 v15, v15, v83
	v_add_f32_e32 v15, v15, v84
	v_add_f32_e32 v15, v15, v85
	v_add_f32_e32 v15, v15, v86
	v_add_f32_e32 v15, v15, v87
	v_add_f32_e32 v15, v15, v88
	v_add_f32_e32 v15, v15, v89
	v_add_f32_e32 v15, v15, v90
	v_add_f32_e32 v15, v15, v91
	v_add_f32_e32 v15, v15, v92
	v_add_f32_e32 v15, v15, v93
	v_add_f32_e32 v15, v15, v94
	v_add_f32_e32 v15, v15, v95
	v_add_f32_e32 v14, v14, v15
	v_add_f32_e32 v143, v143, v14
	v_cvt_pk_bf16_f32 v240, v96, v97
	v_cvt_pk_bf16_f32 v241, v98, v99
	v_cvt_pk_bf16_f32 v242, v100, v101
	v_cvt_pk_bf16_f32 v243, v102, v103
	v_cvt_pk_bf16_f32 v244, v104, v105
	v_cvt_pk_bf16_f32 v245, v106, v107
	v_cvt_pk_bf16_f32 v246, v108, v109
	v_cvt_pk_bf16_f32 v247, v110, v111
	v_cvt_pk_bf16_f32 v248, v80, v81
	v_cvt_pk_bf16_f32 v249, v82, v83
	v_cvt_pk_bf16_f32 v250, v84, v85
	v_cvt_pk_bf16_f32 v251, v86, v87
	v_cvt_pk_bf16_f32 v252, v88, v89
	v_cvt_pk_bf16_f32 v253, v90, v91
	v_cvt_pk_bf16_f32 v254, v92, v93
	v_cvt_pk_bf16_f32 v255, v94, v95
	s_mov_b32 m0, s67
	s_nop 0
	global_load_lds_dwordx4 v156, s[64:65]
	s_mov_b32 m0, s68
	s_nop 0
	global_load_lds_dwordx4 v159, s[64:65]
	s_mov_b32 m0, s69
	s_nop 0
	global_load_lds_dwordx4 v157, s[64:65]
	s_mov_b32 m0, s70
	s_nop 0
	global_load_lds_dwordx4 v158, s[64:65]
	s_nop 1
	s_waitcnt lgkmcnt(10)
	v_mfma_f32_32x32x16_bf16 v[64:79], v[208:211], v[240:243], v[64:79]
	ds_read_b64_tr_b16 v[232:233], v6 offset:28672
	ds_read_b64_tr_b16 v[234:235], v6 offset:29184
	s_waitcnt lgkmcnt(10)
	v_mfma_f32_32x32x16_bf16 v[64:79], v[212:215], v[244:247], v[64:79]
	ds_read_b64_tr_b16 v[236:237], v6 offset:29696
	ds_read_b64_tr_b16 v[238:239], v6 offset:30208
	s_waitcnt lgkmcnt(10)
	v_mfma_f32_32x32x16_bf16 v[48:63], v[216:219], v[240:243], v[48:63]
	ds_read_b64_tr_b16 v[208:209], v6 offset:18432
	ds_read_b64_tr_b16 v[210:211], v6 offset:18944
	s_waitcnt lgkmcnt(10)
	v_mfma_f32_32x32x16_bf16 v[48:63], v[220:223], v[244:247], v[48:63]
	ds_read_b64_tr_b16 v[212:213], v6 offset:19456
	ds_read_b64_tr_b16 v[214:215], v6 offset:19968
	s_waitcnt lgkmcnt(10)
	v_mfma_f32_32x32x16_bf16 v[32:47], v[224:227], v[240:243], v[32:47]
	ds_read_b64_tr_b16 v[216:217], v6 offset:22528
	ds_read_b64_tr_b16 v[218:219], v6 offset:23040
	s_waitcnt lgkmcnt(10)
	v_mfma_f32_32x32x16_bf16 v[32:47], v[228:231], v[244:247], v[32:47]
	ds_read_b64_tr_b16 v[220:221], v6 offset:23552
	ds_read_b64_tr_b16 v[222:223], v6 offset:24064
	s_waitcnt lgkmcnt(10)
	v_mfma_f32_32x32x16_bf16 v[16:31], v[232:235], v[240:243], v[16:31]
	ds_read_b64_tr_b16 v[224:225], v6 offset:26624
	ds_read_b64_tr_b16 v[226:227], v6 offset:27136
	s_waitcnt lgkmcnt(10)
	v_mfma_f32_32x32x16_bf16 v[16:31], v[236:239], v[244:247], v[16:31]
	ds_read_b64_tr_b16 v[228:229], v6 offset:27648
	ds_read_b64_tr_b16 v[230:231], v6 offset:28160
	s_waitcnt lgkmcnt(10)
	v_mfma_f32_32x32x16_bf16 v[64:79], v[208:211], v[248:251], v[64:79]
	ds_read_b64_tr_b16 v[232:233], v6 offset:30720
	ds_read_b64_tr_b16 v[234:235], v6 offset:31232
	s_waitcnt lgkmcnt(10)
	v_mfma_f32_32x32x16_bf16 v[64:79], v[212:215], v[252:255], v[64:79]
	ds_read_b64_tr_b16 v[236:237], v6 offset:31744
	ds_read_b64_tr_b16 v[238:239], v6 offset:32256
	s_waitcnt lgkmcnt(10)
	v_mfma_f32_32x32x16_bf16 v[48:63], v[216:219], v[248:251], v[48:63]
	s_waitcnt lgkmcnt(8)
	v_mfma_f32_32x32x16_bf16 v[48:63], v[220:223], v[252:255], v[48:63]
	s_waitcnt lgkmcnt(6)
	v_mfma_f32_32x32x16_bf16 v[32:47], v[224:227], v[248:251], v[32:47]
	s_waitcnt lgkmcnt(4)
	v_mfma_f32_32x32x16_bf16 v[32:47], v[228:231], v[252:255], v[32:47]
	s_waitcnt lgkmcnt(2)
	v_mfma_f32_32x32x16_bf16 v[16:31], v[232:235], v[248:251], v[16:31]
	s_waitcnt lgkmcnt(0)
	v_mfma_f32_32x32x16_bf16 v[16:31], v[236:239], v[252:255], v[16:31]
	s_branch .Ldf1a_bar

; DI f32x16 mfma32(bf16x8 a, bf16x8 b, f32x16 c) { return __builtin_amdgcn_mfma_f32_32x32x16_bf16(a, b, c, 0, 0, 0); }
; #define DF_VLD(VF, VOFF, H) do { _Pragma("unroll") for (int d2 = 0; d2 < 2; ++d2) { LAS unsigned char* vb_ = lds3 + (VOFF) + (2 * (H) + d2) * 4096; VF[2 * d2] = vfrag(vb_); VF[2 * d2 + 1] = vfrag(vb_ + 1024); } } while (0)
; #define DF_PVM(VF, P0, P1, H) do { _Pragma("unroll") for (int d2 = 0; d2 < 2; ++d2) { o[2 * (H) + d2] = mfma32(VF[2 * d2], P0, o[2 * (H) + d2]); o[2 * (H) + d2] = mfma32(VF[2 * d2 + 1], P1, o[2 * (H) + d2]); } } while (0)
; DI void diff_stage(const unsigned char* lds, LAS unsigned char* lds3, int buf, int t, int comp, int q0, int r32, int hi, int vlane, bool skew,
;                    const bf16x8 (&qf)[4], f32x16 (&o)[4], float& m, float& l, bf16x8 (&pp)[4], int& pvo, bool& have_prev) {
;     const int k0 = 64 * t;
;     if (k0 > q0 + 31) return;
;     const unsigned char* sb = lds + buf * DF_STAGE + comp * DF_K2 + r32 * 128; const int ke16 = (hi ^ ((r32 >> 1) & 7)) * 16;
;     bf16x8 vf[4];
;     if (skew && have_prev) {
; #pragma unroll
;         for (int sub = 0; sub < 2; ++sub) { DF_VLD(vf, pvo + sub * 2048, 0); DF_PVM(vf, pp[2 * sub], pp[2 * sub + 1], 0); DF_VLD(vf, pvo + sub * 2048, 1); DF_PVM(vf, pp[2 * sub], pp[2 * sub + 1], 1); }
;     }
;     f32x16 s0, s1;
; #pragma unroll
;     for (int i = 0; i < 16; ++i) { s0[i] = 0.f; s1[i] = 0.f; }
;     {
;         bf16x8 k0f[4], k1f[4];
; #pragma unroll
;         for (int c = 0; c < 4; ++c) { k0f[c] = *(const bf16x8*)(sb + ((32 * c) ^ ke16)); k1f[c] = *(const bf16x8*)(sb + 32 * 128 + ((32 * c) ^ ke16)); }
; #pragma unroll
;         for (int c = 0; c < 4; ++c) { s0 = mfma32(k0f[c], qf[c], s0); s1 = mfma32(k1f[c], qf[c], s1); }
;     }
;     if (k0 + 63 > q0) {
;         const int dq = q0 + r32 - k0 - 4 * hi;
; #pragma unroll
;         for (int i = 0; i < 16; ++i) { const int ci = (i & 3) + 8 * (i >> 2); s0[i] = (ci > dq) ? -INFINITY : s0[i]; s1[i] = (ci + 32 > dq) ? -INFINITY : s1[i]; }
;     }
.Ldf2a_loop:
	s_sub_i32 s71, s27, 63
	s_cmp_gt_u32 s71, s49
	s_cbranch_scc1 .Ldf2a_skip
	s_and_b32 s31, s26, 0x18000
	v_add_u32_e32 v2, s31, v160
	v_add_u32_e32 v3, v2, v161
	v_add_u32_e32 v4, v2, v162
	v_add_u32_e32 v5, v2, v163
	v_add_u32_e32 v2, v2, v164
	ds_read_b128 v[208:211], v3
	ds_read_b128 v[212:215], v3 offset:4096
	ds_read_b128 v[216:219], v4
	ds_read_b128 v[220:223], v4 offset:4096
	ds_read_b128 v[224:227], v5
	ds_read_b128 v[228:231], v5 offset:4096
	ds_read_b128 v[232:235], v2
	ds_read_b128 v[236:239], v2 offset:4096
	v_add_u32_e32 v6, s31, v165
	s_waitcnt lgkmcnt(7)
	v_mfma_f32_32x32x16_bf16 v[96:111], v[208:211], v[124:127], 0
	s_waitcnt lgkmcnt(6)
	v_mfma_f32_32x32x16_bf16 v[80:95], v[212:215], v[124:127], 0
	s_waitcnt lgkmcnt(5)
	v_mfma_f32_32x32x16_bf16 v[96:111], v[216:219], v[120:123], v[96:111]
	s_waitcnt lgkmcnt(4)
	v_mfma_f32_32x32x16_bf16 v[80:95], v[220:223], v[120:123], v[80:95]
	s_waitcnt lgkmcnt(3)
	v_mfma_f32_32x32x16_bf16 v[96:111], v[224:227], v[116:119], v[96:111]
	s_waitcnt lgkmcnt(2)
	v_mfma_f32_32x32x16_bf16 v[80:95], v[228:231], v[116:119], v[80:95]
	s_waitcnt lgkmcnt(1)
	v_mfma_f32_32x32x16_bf16 v[96:111], v[232:235], v[112:115], v[96:111]
	s_waitcnt lgkmcnt(0)
	v_mfma_f32_32x32x16_bf16 v[80:95], v[236:239], v[112:115], v[80:95]
	ds_read_b64_tr_b16 v[208:209], v6 offset:16384
	ds_read_b64_tr_b16 v[210:211], v6 offset:16896
	ds_read_b64_tr_b16 v[212:213], v6 offset:17408
	ds_read_b64_tr_b16 v[214:215], v6 offset:17920
	ds_read_b64_tr_b16 v[216:217], v6 offset:20480
	ds_read_b64_tr_b16 v[218:219], v6 offset:20992
	ds_read_b64_tr_b16 v[220:221], v6 offset:21504
	ds_read_b64_tr_b16 v[222:223], v6 offset:22016
	ds_read_b64_tr_b16 v[224:225], v6 offset:24576
	ds_read_b64_tr_b16 v[226:227], v6 offset:25088
	ds_read_b64_tr_b16 v[228:229], v6 offset:25600
	ds_read_b64_tr_b16 v[230:231], v6 offset:26112
	s_cmp_le_u32 s27, s10
	s_cbranch_scc1 .Ldf2a_nodiag
	s_nop 7
	v_cmp_lt_i32_e32 vcc, -1, v183
	s_nop 1
	v_cndmask_b32_e32 v96, v176, v96, vcc
	v_cmp_lt_i32_e32 vcc, 31, v183
	s_nop 1
	v_cndmask_b32_e32 v80, v176, v80, vcc
	v_cmp_lt_i32_e32 vcc, 0, v183
	s_nop 1
	v_cndmask_b32_e32 v97, v176, v97, vcc
	v_cmp_lt_i32_e32 vcc, 32, v183
	s_nop 1
	v_cndmask_b32_e32 v81, v176, v81, vcc
	v_cmp_lt_i32_e32 vcc, 1, v183
	s_nop 1
	v_cndmask_b32_e32 v98, v176, v98, vcc
	v_cmp_lt_i32_e32 vcc, 33, v183
	s_nop 1
	v_cndmask_b32_e32 v82, v176, v82, vcc
	v_cmp_lt_i32_e32 vcc, 2, v183
	s_nop 1
	v_cndmask_b32_e32 v99, v176, v99, vcc
	v_cmp_lt_i32_e32 vcc, 34, v183
	s_nop 1
	v_cndmask_b32_e32 v83, v176, v83, vcc
	v_cmp_lt_i32_e32 vcc, 7, v183
	s_nop 1
	v_cndmask_b32_e32 v100, v176, v100, vcc
	v_cmp_lt_i32_e32 vcc, 39, v183
	s_nop 1
	v_cndmask_b32_e32 v84, v176, v84, vcc
	v_cmp_lt_i32_e32 vcc, 8, v183
	s_nop 1
	v_cndmask_b32_e32 v101, v176, v101, vcc
	v_cmp_lt_i32_e32 vcc, 40, v183
	s_nop 1
	v_cndmask_b32_e32 v85, v176, v85, vcc
	v_cmp_lt_i32_e32 vcc, 9, v183
	s_nop 1
	v_cndmask_b32_e32 v102, v176, v102, vcc
	v_cmp_lt_i32_e32 vcc, 41, v183
	s_nop 1
	v_cndmask_b32_e32 v86, v176, v86, vcc
	v_cmp_lt_i32_e32 vcc, 10, v183
	s_nop 1
	v_cndmask_b32_e32 v103, v176, v103, vcc
	v_cmp_lt_i32_e32 vcc, 42, v183
	s_nop 1
	v_cndmask_b32_e32 v87, v176, v87, vcc
	v_cmp_lt_i32_e32 vcc, 15, v183
	s_nop 1
	v_cndmask_b32_e32 v104, v176, v104, vcc
	v_cmp_lt_i32_e32 vcc, 47, v183
	s_nop 1
	v_cndmask_b32_e32 v88, v176, v88, vcc
	v_cmp_lt_i32_e32 vcc, 16, v183
	s_nop 1
	v_cndmask_b32_e32 v105, v176, v105, vcc
	v_cmp_lt_i32_e32 vcc, 48, v183
	s_nop 1
	v_cndmask_b32_e32 v89, v176, v89, vcc
	v_cmp_lt_i32_e32 vcc, 17, v183
	s_nop 1
	v_cndmask_b32_e32 v106, v176, v106, vcc
	v_cmp_lt_i32_e32 vcc, 49, v183
	s_nop 1
	v_cndmask_b32_e32 v90, v176, v90, vcc
	v_cmp_lt_i32_e32 vcc, 18, v183
	s_nop 1
	v_cndmask_b32_e32 v107, v176, v107, vcc
	v_cmp_lt_i32_e32 vcc, 50, v183
	s_nop 1
	v_cndmask_b32_e32 v91, v176, v91, vcc
	v_cmp_lt_i32_e32 vcc, 23, v183
	s_nop 1
	v_cndmask_b32_e32 v108, v176, v108, vcc
	v_cmp_lt_i32_e32 vcc, 55, v183
	s_nop 1
	v_cndmask_b32_e32 v92, v176, v92, vcc
	v_cmp_lt_i32_e32 vcc, 24, v183
	s_nop 1
	v_cndmask_b32_e32 v109, v176, v109, vcc
	v_cmp_lt_i32_e32 vcc, 56, v183
	s_nop 1
	v_cndmask_b32_e32 v93, v176, v93, vcc
	v_cmp_lt_i32_e32 vcc, 25, v183
	s_nop 1
	v_cndmask_b32_e32 v110, v176, v110, vcc
	v_cmp_lt_i32_e32 vcc, 57, v183
	s_nop 1
	v_cndmask_b32_e32 v94, v176, v94, vcc
	v_cmp_lt_i32_e32 vcc, 26, v183
	s_nop 1
	v_cndmask_b32_e32 v111, v176, v111, vcc
	v_cmp_lt_i32_e32 vcc, 58, v183
	s_nop 1
	v_cndmask_b32_e32 v95, v176, v95, vcc

; DI float fexp2(float x) { return __builtin_amdgcn_exp2f(x); }
; #define DF_VLD(VF, VOFF, H) do { _Pragma("unroll") for (int d2 = 0; d2 < 2; ++d2) { LAS unsigned char* vb_ = lds3 + (VOFF) + (2 * (H) + d2) * 4096; VF[2 * d2] = vfrag(vb_); VF[2 * d2 + 1] = vfrag(vb_ + 1024); } } while (0)
; #define DF_PVM(VF, P0, P1, H) do { _Pragma("unroll") for (int d2 = 0; d2 < 2; ++d2) { o[2 * (H) + d2] = mfma32(VF[2 * d2], P0, o[2 * (H) + d2]); o[2 * (H) + d2] = mfma32(VF[2 * d2 + 1], P1, o[2 * (H) + d2]); } } while (0)
; DI void diff_stage(const unsigned char* lds, LAS unsigned char* lds3, int buf, int t, int comp, int q0, int r32, int hi, int vlane, bool skew,
;                    const bf16x8 (&qf)[4], f32x16 (&o)[4], float& m, float& l, bf16x8 (&pp)[4], int& pvo, bool& have_prev) {
;     ...
;     float sum0 = 0.f, sum1 = 0.f;
; #pragma unroll
;     for (int i = 0; i < 16; ++i) { s0[i] = fexp2(__builtin_fmaf(s0[i], SCL2, -m)); sum0 += s0[i]; s1[i] = fexp2(__builtin_fmaf(s1[i], SCL2, -m)); sum1 += s1[i]; }
;     l += sum0 + sum1;
;     const int vo = buf * DF_STAGE + DF_V + vlane;
;     if (!skew) {
;         const bf16x8 p00 = packP<0>(s0), p01 = packP<1>(s0);
;         DF_VLD(vf, vo, 0); DF_PVM(vf, p00, p01, 0); DF_VLD(vf, vo, 1); DF_PVM(vf, p00, p01, 1);
;         const bf16x8 p10 = packP<0>(s1), p11 = packP<1>(s1);
;         DF_VLD(vf, vo + 2048, 0); DF_PVM(vf, p10, p11, 0); DF_VLD(vf, vo + 2048, 1); DF_PVM(vf, p10, p11, 1);
.Ldf2a_notrig:
	v_fma_f32 v96, v96, s44, -v185
	v_fma_f32 v97, v97, s44, -v185
	v_exp_f32_e32 v96, v96
	v_exp_f32_e32 v97, v97
	v_fma_f32 v98, v98, s44, -v185
	v_fma_f32 v99, v99, s44, -v185
	v_exp_f32_e32 v98, v98
	v_exp_f32_e32 v99, v99
	v_fma_f32 v100, v100, s44, -v185
	v_fma_f32 v101, v101, s44, -v185
	v_exp_f32_e32 v100, v100
	v_exp_f32_e32 v101, v101
	v_fma_f32 v102, v102, s44, -v185
	v_fma_f32 v103, v103, s44, -v185
	v_exp_f32_e32 v102, v102
	v_exp_f32_e32 v103, v103
	v_fma_f32 v104, v104, s44, -v185
	v_fma_f32 v105, v105, s44, -v185
	v_exp_f32_e32 v104, v104
	v_exp_f32_e32 v105, v105
	v_fma_f32 v106, v106, s44, -v185
	v_fma_f32 v107, v107, s44, -v185
	v_exp_f32_e32 v106, v106
	v_exp_f32_e32 v107, v107
	v_fma_f32 v108, v108, s44, -v185
	v_fma_f32 v109, v109, s44, -v185
	v_exp_f32_e32 v108, v108
	v_exp_f32_e32 v109, v109
	v_fma_f32 v110, v110, s44, -v185
	v_fma_f32 v111, v111, s44, -v185
	v_exp_f32_e32 v110, v110
	v_exp_f32_e32 v111, v111
	v_add_f32_e32 v14, v96, v97
	v_add_f32_e32 v14, v14, v98
	v_add_f32_e32 v14, v14, v99
	v_add_f32_e32 v14, v14, v100
	v_add_f32_e32 v14, v14, v101
	v_add_f32_e32 v14, v14, v102
	v_add_f32_e32 v14, v14, v103
	v_add_f32_e32 v14, v14, v104
	v_add_f32_e32 v14, v14, v105
	v_add_f32_e32 v14, v14, v106
	v_add_f32_e32 v14, v14, v107
	v_add_f32_e32 v14, v14, v108
	v_add_f32_e32 v14, v14, v109
	v_add_f32_e32 v14, v14, v110
	v_add_f32_e32 v14, v14, v111
	v_fma_f32 v80, v80, s44, -v185
	v_fma_f32 v81, v81, s44, -v185
	v_exp_f32_e32 v80, v80
	v_exp_f32_e32 v81, v81
	v_fma_f32 v82, v82, s44, -v185
	v_fma_f32 v83, v83, s44, -v185
	v_exp_f32_e32 v82, v82
	v_exp_f32_e32 v83, v83
	v_fma_f32 v84, v84, s44, -v185
	v_fma_f32 v85, v85, s44, -v185
	v_exp_f32_e32 v84, v84
	v_exp_f32_e32 v85, v85
	v_fma_f32 v86, v86, s44, -v185
	v_fma_f32 v87, v87, s44, -v185
	v_exp_f32_e32 v86, v86
	v_exp_f32_e32 v87, v87
	v_fma_f32 v88, v88, s44, -v185
	v_fma_f32 v89, v89, s44, -v185
	v_exp_f32_e32 v88, v88
	v_exp_f32_e32 v89, v89
	v_fma_f32 v90, v90, s44, -v185
	v_fma_f32 v91, v91, s44, -v185
	v_exp_f32_e32 v90, v90
	v_exp_f32_e32 v91, v91
	v_fma_f32 v92, v92, s44, -v185
	v_fma_f32 v93, v93, s44, -v185
	v_exp_f32_e32 v92, v92
	v_exp_f32_e32 v93, v93
	v_fma_f32 v94, v94, s44, -v185
	v_fma_f32 v95, v95, s44, -v185
	v_exp_f32_e32 v94, v94
	v_exp_f32_e32 v95, v95
	v_add_f32_e32 v15, v80, v81
	v_add_f32_e32 v15, v15, v82
	v_add_f32_e32 v15, v15, v83
	v_add_f32_e32 v15, v15, v84
	v_add_f32_e32 v15, v15, v85
	v_add_f32_e32 v15, v15, v86
	v_add_f32_e32 v15, v15, v87
	v_add_f32_e32 v15, v15, v88
	v_add_f32_e32 v15, v15, v89
	v_add_f32_e32 v15, v15, v90
	v_add_f32_e32 v15, v15, v91
	v_add_f32_e32 v15, v15, v92
	v_add_f32_e32 v15, v15, v93
	v_add_f32_e32 v15, v15, v94
	v_add_f32_e32 v15, v15, v95
	v_add_f32_e32 v14, v14, v15
	v_add_f32_e32 v143, v143, v14
	v_cvt_pk_bf16_f32 v240, v96, v97
	v_cvt_pk_bf16_f32 v241, v98, v99
	v_cvt_pk_bf16_f32 v242, v100, v101
	v_cvt_pk_bf16_f32 v243, v102, v103
	v_cvt_pk_bf16_f32 v244, v104, v105
	v_cvt_pk_bf16_f32 v245, v106, v107
	v_cvt_pk_bf16_f32 v246, v108, v109
	v_cvt_pk_bf16_f32 v247, v110, v111
	v_cvt_pk_bf16_f32 v248, v80, v81
	v_cvt_pk_bf16_f32 v249, v82, v83
	v_cvt_pk_bf16_f32 v250, v84, v85
	v_cvt_pk_bf16_f32 v251, v86, v87
	v_cvt_pk_bf16_f32 v252, v88, v89
	v_cvt_pk_bf16_f32 v253, v90, v91
	v_cvt_pk_bf16_f32 v254, v92, v93
	v_cvt_pk_bf16_f32 v255, v94, v95
	s_mov_b32 m0, s67
	s_nop 0
	global_load_lds_dwordx4 v156, s[64:65]
	s_mov_b32 m0, s68
	s_nop 0
	global_load_lds_dwordx4 v159, s[64:65]
	s_mov_b32 m0, s69
	s_nop 0
	global_load_lds_dwordx4 v157, s[64:65]
	s_mov_b32 m0, s70
	s_nop 0
	global_load_lds_dwordx4 v158, s[64:65]
	s_nop 1
	s_waitcnt lgkmcnt(10)
	v_mfma_f32_32x32x16_bf16 v[64:79], v[208:211], v[240:243], v[64:79]
	ds_read_b64_tr_b16 v[232:233], v6 offset:28672
	ds_read_b64_tr_b16 v[234:235], v6 offset:29184
	s_waitcnt lgkmcnt(10)
	v_mfma_f32_32x32x16_bf16 v[64:79], v[212:215], v[244:247], v[64:79]
	ds_read_b64_tr_b16 v[236:237], v6 offset:29696
	ds_read_b64_tr_b16 v[238:239], v6 offset:30208
	s_waitcnt lgkmcnt(10)
	v_mfma_f32_32x32x16_bf16 v[48:63], v[216:219], v[240:243], v[48:63]
	ds_read_b64_tr_b16 v[208:209], v6 offset:18432
	ds_read_b64_tr_b16 v[210:211], v6 offset:18944
	s_waitcnt lgkmcnt(10)
	v_mfma_f32_32x32x16_bf16 v[48:63], v[220:223], v[244:247], v[48:63]
	ds_read_b64_tr_b16 v[212:213], v6 offset:19456
	ds_read_b64_tr_b16 v[214:215], v6 offset:19968
	s_waitcnt lgkmcnt(10)
	v_mfma_f32_32x32x16_bf16 v[32:47], v[224:227], v[240:243], v[32:47]
	ds_read_b64_tr_b16 v[216:217], v6 offset:22528
	ds_read_b64_tr_b16 v[218:219], v6 offset:23040
	s_waitcnt lgkmcnt(10)
	v_mfma_f32_32x32x16_bf16 v[32:47], v[228:231], v[244:247], v[32:47]
	ds_read_b64_tr_b16 v[220:221], v6 offset:23552
	ds_read_b64_tr_b16 v[222:223], v6 offset:24064
	s_waitcnt lgkmcnt(10)
	v_mfma_f32_32x32x16_bf16 v[16:31], v[232:235], v[240:243], v[16:31]
	ds_read_b64_tr_b16 v[224:225], v6 offset:26624
	ds_read_b64_tr_b16 v[226:227], v6 offset:27136
	s_waitcnt lgkmcnt(10)
	v_mfma_f32_32x32x16_bf16 v[16:31], v[236:239], v[244:247], v[16:31]
	ds_read_b64_tr_b16 v[228:229], v6 offset:27648
	ds_read_b64_tr_b16 v[230:231], v6 offset:28160
	s_waitcnt lgkmcnt(10)
	v_mfma_f32_32x32x16_bf16 v[64:79], v[208:211], v[248:251], v[64:79]
	ds_read_b64_tr_b16 v[232:233], v6 offset:30720
	ds_read_b64_tr_b16 v[234:235], v6 offset:31232
	s_waitcnt lgkmcnt(10)
	v_mfma_f32_32x32x16_bf16 v[64:79], v[212:215], v[252:255], v[64:79]
	ds_read_b64_tr_b16 v[236:237], v6 offset:31744
	ds_read_b64_tr_b16 v[238:239], v6 offset:32256
	s_waitcnt lgkmcnt(10)
	v_mfma_f32_32x32x16_bf16 v[48:63], v[216:219], v[248:251], v[48:63]
	s_waitcnt lgkmcnt(8)
	v_mfma_f32_32x32x16_bf16 v[48:63], v[220:223], v[252:255], v[48:63]
	s_waitcnt lgkmcnt(6)
	v_mfma_f32_32x32x16_bf16 v[32:47], v[224:227], v[248:251], v[32:47]
	s_waitcnt lgkmcnt(4)
	v_mfma_f32_32x32x16_bf16 v[32:47], v[228:231], v[252:255], v[32:47]
	s_waitcnt lgkmcnt(2)
	v_mfma_f32_32x32x16_bf16 v[16:31], v[232:235], v[248:251], v[16:31]
	s_waitcnt lgkmcnt(0)
	v_mfma_f32_32x32x16_bf16 v[16:31], v[236:239], v[252:255], v[16:31]
	s_branch .Ldf2a_bar
